# grid barrier: the L1/L2 invalidate (acquire) is issued by a second wave right after the entry barrier so it overlaps the arrival/release chain (one workgroup per CU, no loads after entry)
# speedup vs baseline: 1.0080x; 1.0027x over previous
.LBB0_546:
	s_or_b64 exec, exec, s[4:5]
	s_getreg_b32 s4, hwreg(HW_REG_XCC_ID, 0, 4)
	s_waitcnt vmcnt(0)
	s_waitcnt lgkmcnt(0)
	s_barrier
	v_readfirstlane_b32 s14, v222
	s_lshr_b32 s14, s14, 6
	s_cmp_eq_u32 s14, 1
	s_cbranch_scc0 .Lbar_noinv
	buffer_inv sc1
	s_waitcnt vmcnt(0)
.Lbar_noinv:
	s_mov_b64 s[10:11], exec
	v_readlane_b32 s12, v254, 58
	v_readlane_b32 s13, v254, 59
	s_and_b64 s[12:13], s[10:11], s[12:13]
	s_mov_b64 exec, s[12:13]
	s_cbranch_execz .LBB0_11
	s_add_i32 s21, 0, 0x20000
	v_mov_b32_e32 v0, s21
	s_waitcnt vmcnt(0) expcnt(0) lgkmcnt(0)
	ds_read_b32 v2, v0
	v_readlane_b32 s5, v254, 53
	s_and_b32 s7, s4, 15
	s_waitcnt lgkmcnt(0)
	v_cmp_ne_u32_e32 vcc, 0, v2
	v_mov_b32_e32 v0, s5
	ds_read_b32 v0, v0
	s_cbranch_vccnz .LBB0_562
	s_load_dwordx2 s[14:15], s[48:49], 0x4
	s_add_u32 s4, s90, 0x20200
	s_addc_u32 s5, s91, 0
	s_add_u32 s12, s90, 0x20400
	s_addc_u32 s13, s91, 0
	s_waitcnt lgkmcnt(0)
	s_mul_i32 s6, s14, s6
	s_add_u32 s14, s90, 0x20500
	s_mul_i32 s6, s6, s15
	s_addc_u32 s15, s91, 0
	s_add_u32 s16, s90, 0x20600
	s_addc_u32 s17, s91, 0
	s_add_u32 s18, s90, 0x20700
	s_addc_u32 s19, s91, 0
	s_add_u32 s30, s90, 0x20800
	s_addc_u32 s31, s91, 0
	s_add_u32 s34, s90, 0x20900
	s_addc_u32 s35, s91, 0
	s_add_u32 s36, s90, 0x20a00
	s_addc_u32 s37, s91, 0
	s_add_u32 s38, s90, 0x20b00
	s_addc_u32 s39, s91, 0
	s_add_u32 s40, s90, 0x20c00
	s_addc_u32 s41, s91, 0
	s_add_u32 s46, s90, 0x20d00
	s_addc_u32 s47, s91, 0
	s_add_u32 s48, s90, 0x20e00
	s_addc_u32 s49, s91, 0
	s_add_u32 s50, s90, 0x20f00
	s_addc_u32 s51, s91, 0
	s_add_u32 s52, s90, 0x21000
	s_addc_u32 s53, s91, 0
	s_add_u32 s54, s90, 0x21100
	s_addc_u32 s55, s91, 0
	s_add_u32 s56, s90, 0x21200
	s_addc_u32 s57, s91, 0
	s_add_u32 s58, s90, 0x21300
	s_addc_u32 s59, s91, 0
	s_mov_b32 s33, 1
	s_branch .LBB0_550

.LBB0_577:
	s_or_b64 exec, exec, s[14:15]
	s_waitcnt vmcnt(0)
	s_waitcnt vmcnt(0)

.LBB0_595:
	s_or_b64 exec, exec, s[4:5]
	s_mov_b64 s[4:5], exec
	v_mbcnt_lo_u32_b32 v0, s4, 0
	v_mbcnt_hi_u32_b32 v0, s5, v0
	v_cmp_eq_u32_e32 vcc, 0, v0
	s_waitcnt vmcnt(0)
	s_and_saveexec_b64 s[14:15], vcc
	s_cbranch_execz .LBB0_10
	s_bcnt1_i32_b64 s4, s[4:5]
	v_mov_b32_e32 v0, s4
	global_atomic_add v237, v0, s[12:13] offset:1024
	s_branch .LBB0_10
